# rstd in the w_in and ffn2 gate/up GEMM epilogues via v_rsq_f32; counted vmcnt waits in the banded attention tile loop
# baseline (speedup 1.0000x reference)
; __device__ __forceinline__ unsigned cvt_pk_bf16(float lo, float hi) { unsigned r; asm volatile("v_cvt_pk_bf16_f32 %0, %1, %2" : "=v"(r) : "v"(lo), "v"(hi)); return r; }
;     __device__ __forceinline__ void operator()(const f32x4 (&acc)[2][2][4][2], const Unit& u, int wr, int wc, int fr, int fq) const {
;         const int row0 = u.pm * BM + wr * 64 + fr; const int col0 = u.pn * BM + wc * 32 + 8 * fq;
; #pragma unroll
;         for (int ai = 0; ai < 2; ++ai)
; #pragma unroll
;             for (int m = 0; m < 4; ++m) { const int row = row0 + ai * HALF + m * 16; bf16_t* rowp = O + (size_t)row * ldc + col0;
;                 float rs = 1.0f; if constexpr (NORM) rs = 1.0f / sqrtf(ss[row] * (1.0f / 2048.0f) + 1e-6f);
; #pragma unroll
;                 for (int bj = 0; bj < 2; ++bj) { const f32x4 v0 = acc[ai][bj][m][0] * rs, v1 = acc[ai][bj][m][1] * rs;
;                     u32x4 w; w.x = cvt_pk_bf16(v0[0], v0[1]); w.y = cvt_pk_bf16(v0[2], v0[3]); w.z = cvt_pk_bf16(v1[0], v1[1]); w.w = cvt_pk_bf16(v1[2], v1[3]);
;                     *(u32x4*)(rowp + bj * HALF) = w; } }
.LBB0_349:
	v_lshl_add_u32 v144, s0, 8, v152
	v_ashrrev_i32_e32 v145, 31, v144
	v_lshl_add_u64 v[150:151], v[144:145], 2, s[16:17]
	global_load_dword v145, v[150:151], off
	v_mov_b64_e32 v[146:147], s[14:15]
	v_lshl_or_b32 v148, s1, 8, v154
	v_mad_i64_i32 v[160:161], s[0:1], v144, s72, v[146:147]
	v_or_b32_e32 v162, 16, v144
	v_ashrrev_i32_e32 v149, 31, v148
	v_lshlrev_b64 v[148:149], 1, v[148:149]
	v_lshl_add_u64 v[160:161], v[160:161], 0, v[148:149]
	s_waitcnt vmcnt(0)
	v_fmamk_f32 v145, v145, 0x3a000000, v158
	v_rsq_f32_e32 v166, v145
	s_nop 0
	v_ashrrev_i32_e32 v163, 31, v162
	v_lshl_add_u64 v[164:165], v[162:163], 2, s[16:17]
	v_pk_mul_f32 v[126:127], v[126:127], v[166:167] op_sel_hi:[1,0]
	v_pk_mul_f32 v[124:125], v[124:125], v[166:167] op_sel_hi:[1,0]
	v_pk_mul_f32 v[122:123], v[122:123], v[166:167] op_sel_hi:[1,0]
	v_pk_mul_f32 v[120:121], v[120:121], v[166:167] op_sel_hi:[1,0]
	v_pk_mul_f32 v[118:119], v[118:119], v[166:167] op_sel_hi:[1,0]
	v_pk_mul_f32 v[116:117], v[116:117], v[166:167] op_sel_hi:[1,0]
	v_pk_mul_f32 v[168:169], v[114:115], v[166:167] op_sel_hi:[1,0]
	v_pk_mul_f32 v[166:167], v[112:113], v[166:167] op_sel_hi:[1,0]
	v_cvt_pk_bf16_f32 v112, v124, v125
	v_cvt_pk_bf16_f32 v113, v126, v127
	v_cvt_pk_bf16_f32 v114, v120, v121
	v_cvt_pk_bf16_f32 v115, v122, v123
	global_store_dwordx4 v[160:161], v[112:115], off
	s_nop 1
	v_cvt_pk_bf16_f32 v112, v116, v117
	v_cvt_pk_bf16_f32 v113, v118, v119
	v_cvt_pk_bf16_f32 v114, v166, v167
	v_cvt_pk_bf16_f32 v115, v168, v169
	global_store_dwordx4 v[160:161], v[112:115], off offset:256
	global_load_dword v113, v[164:165], off
	s_nop 0
	v_or_b32_e32 v112, 32, v144
	s_waitcnt vmcnt(0)
	v_fmamk_f32 v113, v113, 0x3a000000, v158
	v_rsq_f32_e32 v118, v113
	s_nop 0
	v_mad_i64_i32 v[114:115], s[0:1], v162, s72, v[146:147]
	v_ashrrev_i32_e32 v113, 31, v112
	v_lshl_add_u64 v[114:115], v[114:115], 0, v[148:149]
	v_lshl_add_u64 v[116:117], v[112:113], 2, s[16:17]
	v_pk_mul_f32 v[110:111], v[110:111], v[118:119] op_sel_hi:[1,0]
	v_pk_mul_f32 v[108:109], v[108:109], v[118:119] op_sel_hi:[1,0]
	v_pk_mul_f32 v[106:107], v[106:107], v[118:119] op_sel_hi:[1,0]
	v_pk_mul_f32 v[104:105], v[104:105], v[118:119] op_sel_hi:[1,0]
	v_pk_mul_f32 v[102:103], v[102:103], v[118:119] op_sel_hi:[1,0]
	v_pk_mul_f32 v[100:101], v[100:101], v[118:119] op_sel_hi:[1,0]
	v_pk_mul_f32 v[120:121], v[98:99], v[118:119] op_sel_hi:[1,0]
	v_pk_mul_f32 v[118:119], v[96:97], v[118:119] op_sel_hi:[1,0]
	v_cvt_pk_bf16_f32 v96, v108, v109
	v_cvt_pk_bf16_f32 v97, v110, v111
	v_cvt_pk_bf16_f32 v98, v104, v105
	v_cvt_pk_bf16_f32 v99, v106, v107
	global_store_dwordx4 v[114:115], v[96:99], off
	s_nop 1
	v_cvt_pk_bf16_f32 v96, v100, v101
	v_cvt_pk_bf16_f32 v97, v102, v103
	v_cvt_pk_bf16_f32 v98, v118, v119
	v_cvt_pk_bf16_f32 v99, v120, v121
	global_store_dwordx4 v[114:115], v[96:99], off offset:256
	global_load_dword v97, v[116:117], off
	s_nop 0
	v_or_b32_e32 v96, 48, v144
	s_waitcnt vmcnt(0)
	v_fmamk_f32 v97, v97, 0x3a000000, v158
	v_rsq_f32_e32 v102, v97
	s_nop 0
	v_mad_i64_i32 v[98:99], s[0:1], v112, s72, v[146:147]
	v_ashrrev_i32_e32 v97, 31, v96
	v_lshl_add_u64 v[98:99], v[98:99], 0, v[148:149]
	v_lshl_add_u64 v[100:101], v[96:97], 2, s[16:17]
	v_pk_mul_f32 v[94:95], v[94:95], v[102:103] op_sel_hi:[1,0]
	v_pk_mul_f32 v[92:93], v[92:93], v[102:103] op_sel_hi:[1,0]
	v_pk_mul_f32 v[90:91], v[90:91], v[102:103] op_sel_hi:[1,0]
	v_pk_mul_f32 v[88:89], v[88:89], v[102:103] op_sel_hi:[1,0]
	v_pk_mul_f32 v[86:87], v[86:87], v[102:103] op_sel_hi:[1,0]
	v_pk_mul_f32 v[84:85], v[84:85], v[102:103] op_sel_hi:[1,0]
	v_pk_mul_f32 v[104:105], v[82:83], v[102:103] op_sel_hi:[1,0]
	v_pk_mul_f32 v[102:103], v[80:81], v[102:103] op_sel_hi:[1,0]
	v_cvt_pk_bf16_f32 v80, v92, v93
	v_cvt_pk_bf16_f32 v81, v94, v95
	v_cvt_pk_bf16_f32 v82, v88, v89
	v_cvt_pk_bf16_f32 v83, v90, v91
	global_store_dwordx4 v[98:99], v[80:83], off
	s_nop 1
	v_cvt_pk_bf16_f32 v80, v84, v85
	v_cvt_pk_bf16_f32 v81, v86, v87
	v_cvt_pk_bf16_f32 v82, v102, v103
	v_cvt_pk_bf16_f32 v83, v104, v105
	global_store_dwordx4 v[98:99], v[80:83], off offset:256
	global_load_dword v80, v[100:101], off
	s_waitcnt vmcnt(0)
	v_fmamk_f32 v80, v80, 0x3a000000, v158
	v_rsq_f32_e32 v82, v80
	s_nop 0
	v_mad_i64_i32 v[80:81], s[0:1], v96, s72, v[146:147]
	v_lshl_add_u64 v[80:81], v[80:81], 0, v[148:149]
	v_pk_mul_f32 v[78:79], v[78:79], v[82:83] op_sel_hi:[1,0]
	v_pk_mul_f32 v[76:77], v[76:77], v[82:83] op_sel_hi:[1,0]
	v_pk_mul_f32 v[74:75], v[74:75], v[82:83] op_sel_hi:[1,0]
	v_pk_mul_f32 v[72:73], v[72:73], v[82:83] op_sel_hi:[1,0]
	v_pk_mul_f32 v[70:71], v[70:71], v[82:83] op_sel_hi:[1,0]
	v_pk_mul_f32 v[68:69], v[68:69], v[82:83] op_sel_hi:[1,0]
	v_pk_mul_f32 v[84:85], v[66:67], v[82:83] op_sel_hi:[1,0]
	v_pk_mul_f32 v[82:83], v[64:65], v[82:83] op_sel_hi:[1,0]
	v_cvt_pk_bf16_f32 v64, v76, v77
	v_cvt_pk_bf16_f32 v65, v78, v79
	v_cvt_pk_bf16_f32 v66, v72, v73
	v_cvt_pk_bf16_f32 v67, v74, v75
	global_store_dwordx4 v[80:81], v[64:67], off
	s_nop 1
	v_cvt_pk_bf16_f32 v64, v68, v69
	v_cvt_pk_bf16_f32 v65, v70, v71
	v_cvt_pk_bf16_f32 v66, v82, v83
	v_cvt_pk_bf16_f32 v67, v84, v85
	global_store_dwordx4 v[80:81], v[64:67], off offset:256
	global_load_dword v64, v[150:151], off offset:512
	s_waitcnt vmcnt(0)
; __device__ __forceinline__ unsigned cvt_pk_bf16(float lo, float hi) { unsigned r; asm volatile("v_cvt_pk_bf16_f32 %0, %1, %2" : "=v"(r) : "v"(lo), "v"(hi)); return r; }
; #define PG8_BAR __builtin_amdgcn_s_barrier()
;     __device__ __forceinline__ void operator()(const f32x4 (&acc)[2][2][4][2], const Unit& u, int wr, int wc, int fr, int fq) const {
;     ...
;             for (int m = 0; m < 4; ++m) { const int row = row0 + ai * HALF + m * 16; bf16_t* rowp = O + (size_t)row * ldc + col0;
;                 float rs = 1.0f; if constexpr (NORM) rs = 1.0f / sqrtf(ss[row] * (1.0f / 2048.0f) + 1e-6f);
; #pragma unroll
;                 for (int bj = 0; bj < 2; ++bj) { const f32x4 v0 = acc[ai][bj][m][0] * rs, v1 = acc[ai][bj][m][1] * rs;
;                     u32x4 w; w.x = cvt_pk_bf16(v0[0], v0[1]); w.y = cvt_pk_bf16(v0[2], v0[3]); w.z = cvt_pk_bf16(v1[0], v1[1]); w.w = cvt_pk_bf16(v1[2], v1[3]);
;                     *(u32x4*)(rowp + bj * HALF) = w; } }
; template <class Epi, class Sched, bool ALIGN_EPI = false, bool SP2 = false>
; __device__ __forceinline__ void gemm_phase(PG8_LAS unsigned char* lds, const Gemm g, const Sched& S, const Epi& E) {
;     ...
;         if (!has_next) break;
; #pragma unroll
;         for (int a = 0; a < 2; ++a)
; #pragma unroll
;             for (int b = 0; b < 2; ++b)
; #pragma unroll
;                 for (int m = 0; m < 4; ++m)
; #pragma unroll
;                     for (int n = 0; n < 2; ++n) acc[a][b][m][n] = (f32x4){0.f, 0.f, 0.f, 0.f};
;         cur = nxt; cA = nA; cB = nB; ++ui;
;         if constexpr (ALIGN_EPI) { if (wr == 1) PG8_BAR; }
	v_fmamk_f32 v64, v64, 0x3a000000, v158
	v_rsq_f32_e32 v66, v64
	s_nop 0
	v_add_u32_e32 v64, 0x80, v144
	v_mad_i64_i32 v[64:65], s[0:1], v64, s72, v[146:147]
	v_lshl_add_u64 v[64:65], v[64:65], 0, v[148:149]
	v_pk_mul_f32 v[62:63], v[62:63], v[66:67] op_sel_hi:[1,0]
	v_pk_mul_f32 v[60:61], v[60:61], v[66:67] op_sel_hi:[1,0]
	v_pk_mul_f32 v[58:59], v[58:59], v[66:67] op_sel_hi:[1,0]
	v_pk_mul_f32 v[56:57], v[56:57], v[66:67] op_sel_hi:[1,0]
	v_pk_mul_f32 v[54:55], v[54:55], v[66:67] op_sel_hi:[1,0]
	v_pk_mul_f32 v[52:53], v[52:53], v[66:67] op_sel_hi:[1,0]
	v_pk_mul_f32 v[68:69], v[50:51], v[66:67] op_sel_hi:[1,0]
	v_pk_mul_f32 v[66:67], v[48:49], v[66:67] op_sel_hi:[1,0]
	v_cvt_pk_bf16_f32 v48, v60, v61
	v_cvt_pk_bf16_f32 v49, v62, v63
	v_cvt_pk_bf16_f32 v50, v56, v57
	v_cvt_pk_bf16_f32 v51, v58, v59
	global_store_dwordx4 v[64:65], v[48:51], off
	s_nop 1
	v_cvt_pk_bf16_f32 v48, v52, v53
	v_cvt_pk_bf16_f32 v49, v54, v55
	v_cvt_pk_bf16_f32 v50, v66, v67
	v_cvt_pk_bf16_f32 v51, v68, v69
	global_store_dwordx4 v[64:65], v[48:51], off offset:256
	global_load_dword v48, v[150:151], off offset:576
	s_waitcnt vmcnt(0)
	v_fmamk_f32 v48, v48, 0x3a000000, v158
	v_rsq_f32_e32 v50, v48
	s_nop 0
	v_add_u32_e32 v48, 0x90, v144
	v_mad_i64_i32 v[48:49], s[0:1], v48, s72, v[146:147]
	v_lshl_add_u64 v[48:49], v[48:49], 0, v[148:149]
	v_pk_mul_f32 v[46:47], v[46:47], v[50:51] op_sel_hi:[1,0]
	v_pk_mul_f32 v[44:45], v[44:45], v[50:51] op_sel_hi:[1,0]
	v_pk_mul_f32 v[42:43], v[42:43], v[50:51] op_sel_hi:[1,0]
	v_pk_mul_f32 v[40:41], v[40:41], v[50:51] op_sel_hi:[1,0]
	v_pk_mul_f32 v[38:39], v[38:39], v[50:51] op_sel_hi:[1,0]
	v_pk_mul_f32 v[36:37], v[36:37], v[50:51] op_sel_hi:[1,0]
	v_pk_mul_f32 v[52:53], v[34:35], v[50:51] op_sel_hi:[1,0]
	v_pk_mul_f32 v[50:51], v[32:33], v[50:51] op_sel_hi:[1,0]
	v_cvt_pk_bf16_f32 v32, v44, v45
	v_cvt_pk_bf16_f32 v33, v46, v47
	v_cvt_pk_bf16_f32 v34, v40, v41
	v_cvt_pk_bf16_f32 v35, v42, v43
	global_store_dwordx4 v[48:49], v[32:35], off
	s_nop 1
	v_cvt_pk_bf16_f32 v32, v36, v37
	v_cvt_pk_bf16_f32 v33, v38, v39
	v_cvt_pk_bf16_f32 v34, v50, v51
	v_cvt_pk_bf16_f32 v35, v52, v53
	global_store_dwordx4 v[48:49], v[32:35], off offset:256
	global_load_dword v32, v[150:151], off offset:640
	s_waitcnt vmcnt(0)
	v_fmamk_f32 v32, v32, 0x3a000000, v158
	v_rsq_f32_e32 v34, v32
	s_nop 0
	v_add_u32_e32 v32, 0xa0, v144
	v_mad_i64_i32 v[32:33], s[0:1], v32, s72, v[146:147]
	v_lshl_add_u64 v[32:33], v[32:33], 0, v[148:149]
	v_pk_mul_f32 v[30:31], v[30:31], v[34:35] op_sel_hi:[1,0]
	v_pk_mul_f32 v[28:29], v[28:29], v[34:35] op_sel_hi:[1,0]
	v_pk_mul_f32 v[26:27], v[26:27], v[34:35] op_sel_hi:[1,0]
	v_pk_mul_f32 v[24:25], v[24:25], v[34:35] op_sel_hi:[1,0]
	v_pk_mul_f32 v[22:23], v[22:23], v[34:35] op_sel_hi:[1,0]
	v_pk_mul_f32 v[20:21], v[20:21], v[34:35] op_sel_hi:[1,0]
	v_pk_mul_f32 v[36:37], v[18:19], v[34:35] op_sel_hi:[1,0]
	v_pk_mul_f32 v[34:35], v[16:17], v[34:35] op_sel_hi:[1,0]
	v_cvt_pk_bf16_f32 v16, v28, v29
	v_cvt_pk_bf16_f32 v17, v30, v31
	v_cvt_pk_bf16_f32 v18, v24, v25
	v_cvt_pk_bf16_f32 v19, v26, v27
	global_store_dwordx4 v[32:33], v[16:19], off
	s_nop 1
	v_cvt_pk_bf16_f32 v16, v20, v21
	v_cvt_pk_bf16_f32 v17, v22, v23
	v_cvt_pk_bf16_f32 v18, v34, v35
	v_cvt_pk_bf16_f32 v19, v36, v37
	global_store_dwordx4 v[32:33], v[16:19], off offset:256
	global_load_dword v16, v[150:151], off offset:704
	s_nop 0
	v_add_u32_e32 v17, 0xb0, v144
	s_waitcnt vmcnt(0)
	v_fmamk_f32 v16, v16, 0x3a000000, v158
	v_rsq_f32_e32 v18, v16
	s_nop 0
	v_mad_i64_i32 v[16:17], s[0:1], v17, s72, v[146:147]
	v_lshl_add_u64 v[16:17], v[16:17], 0, v[148:149]
	s_mov_b64 s[0:1], -1
	s_andn2_b64 vcc, exec, s[2:3]
	v_pk_mul_f32 v[14:15], v[14:15], v[18:19] op_sel_hi:[1,0]
	v_pk_mul_f32 v[12:13], v[12:13], v[18:19] op_sel_hi:[1,0]
	v_pk_mul_f32 v[10:11], v[10:11], v[18:19] op_sel_hi:[1,0]
	v_pk_mul_f32 v[8:9], v[8:9], v[18:19] op_sel_hi:[1,0]
	v_pk_mul_f32 v[6:7], v[6:7], v[18:19] op_sel_hi:[1,0]
	v_pk_mul_f32 v[4:5], v[4:5], v[18:19] op_sel_hi:[1,0]
	v_pk_mul_f32 v[20:21], v[2:3], v[18:19] op_sel_hi:[1,0]
	v_pk_mul_f32 v[18:19], v[0:1], v[18:19] op_sel_hi:[1,0]
	v_cvt_pk_bf16_f32 v0, v12, v13
	v_cvt_pk_bf16_f32 v1, v14, v15
	v_cvt_pk_bf16_f32 v2, v8, v9
	v_cvt_pk_bf16_f32 v3, v10, v11
	global_store_dwordx4 v[16:17], v[0:3], off
	s_nop 1
	v_cvt_pk_bf16_f32 v0, v4, v5
	v_cvt_pk_bf16_f32 v1, v6, v7
	v_cvt_pk_bf16_f32 v2, v18, v19
	v_cvt_pk_bf16_f32 v3, v20, v21
	global_store_dwordx4 v[16:17], v[0:3], off offset:256
	s_cbranch_vccnz .LBB0_342
	s_andn2_b64 vcc, exec, s[12:13]
	s_cbranch_vccnz .LBB0_341
	s_barrier
	s_branch .LBB0_341

; #define SWRITE(b, i) do { *(bf16x8*)((char*)V_lds + (b) * SHM_V + vst0) = sr_[i].vs0;          \
;     *(bf16x8*)((char*)V_lds + (b) * SHM_V + vst1) = sr_[i].vs1; int kc = sc * 2;               \
;     *(bf16x8*)((char*)K_lds + (b) * SHM_K + KSWZ(sr, kc)) = sr_[i].ks0;                       \
;     *(bf16x8*)((char*)K_lds + (b) * SHM_K + KSWZ(32 + sr, kc)) = sr_[i].ks1; } while (0)
;     ...
;       SWRITE(0, 0); __syncthreads();
;       if (j + 2 < NT) SLOAD(0, j + 2);
.LBB0_516:
	s_cmp_gt_u32 s58, 3
	s_cselect_b64 s[46:47], -1, 0
	s_and_b64 vcc, exec, s[46:47]
	s_waitcnt vmcnt(4)
	ds_write_b128 v206, v[128:131]
	ds_write_b128 v206, v[132:135] offset:8192
	ds_write_b128 v207, v[136:139] offset:32768
	ds_write_b128 v207, v[140:143] offset:40960
	s_waitcnt lgkmcnt(0)
	s_barrier
	s_cbranch_vccnz .LBB0_518
	s_add_i32 s4, s78, 64
	s_cmp_lt_u32 s4, s1
	s_cselect_b32 s4, s4, 0
	s_mul_i32 s48, s28, s4
	s_mul_hi_u32 s49, s28, s4
	s_add_u32 s4, s59, s48
	s_addc_u32 s5, s94, s49
	s_add_u32 s48, s95, s48
	s_addc_u32 s49, s96, s49
	v_lshl_add_u64 v[64:65], s[48:49], 0, v[164:165]
	v_lshl_add_u64 v[66:67], s[48:49], 0, v[166:167]
	global_load_dwordx4 v[128:131], v[64:65], off
	global_load_dwordx4 v[132:135], v[66:67], off
	v_lshl_add_u64 v[64:65], s[4:5], 0, v[164:165]
	v_lshl_add_u64 v[66:67], s[4:5], 0, v[166:167]
	global_load_dwordx4 v[136:139], v[64:65], off
	global_load_dwordx4 v[140:143], v[66:67], off

; #define SWRITE(b, i) do { *(bf16x8*)((char*)V_lds + (b) * SHM_V + vst0) = sr_[i].vs0;          \
;     *(bf16x8*)((char*)V_lds + (b) * SHM_V + vst1) = sr_[i].vs1; int kc = sc * 2;               \
;     *(bf16x8*)((char*)K_lds + (b) * SHM_K + KSWZ(sr, kc)) = sr_[i].ks0;                       \
;     *(bf16x8*)((char*)K_lds + (b) * SHM_K + KSWZ(32 + sr, kc)) = sr_[i].ks1; } while (0)
;     ...
;       SWRITE(1, 1); __syncthreads();
;       if (j + 3 < NT) SLOAD(1, j + 3);
.LBB0_526:
	s_and_b64 vcc, exec, s[46:47]
	s_cbranch_vccnz .Lb_mid_w0
	s_waitcnt vmcnt(4)
	s_branch .Lb_mid_go
.Lb_mid_w0:
	s_waitcnt vmcnt(0)
.Lb_mid_go:
	s_cmp_gt_u32 s58, 2
	ds_write_b128 v206, v[144:147] offset:16384
	ds_write_b128 v206, v[148:151] offset:24576
	ds_write_b128 v207, v[152:155] offset:49152
	ds_write_b128 v207, v[156:159] offset:57344
	s_waitcnt lgkmcnt(0)
	s_barrier
	s_cbranch_scc1 .LBB0_528
	s_add_i32 s4, s78, 0x80
	s_cmp_lt_u32 s4, s1
	s_cselect_b32 s4, s4, 0
	s_mul_i32 s48, s28, s4
	s_mul_hi_u32 s49, s28, s4
	s_add_u32 s4, s59, s48
	s_addc_u32 s5, s94, s49
	s_add_u32 s48, s95, s48
	s_addc_u32 s49, s96, s49
	v_lshl_add_u64 v[64:65], s[48:49], 0, v[164:165]
	v_lshl_add_u64 v[66:67], s[48:49], 0, v[166:167]
	global_load_dwordx4 v[144:147], v[64:65], off
	global_load_dwordx4 v[148:151], v[66:67], off
	v_lshl_add_u64 v[64:65], s[4:5], 0, v[164:165]
	v_lshl_add_u64 v[66:67], s[4:5], 0, v[166:167]
	global_load_dwordx4 v[152:155], v[64:65], off
	global_load_dwordx4 v[156:159], v[66:67], off

; __device__ __forceinline__ unsigned cvt_pk_bf16(float lo, float hi) { unsigned r; asm volatile("v_cvt_pk_bf16_f32 %0, %1, %2" : "=v"(r) : "v"(lo), "v"(hi)); return r; }
;     __device__ __forceinline__ float act(float g, float u) const { const float e = __builtin_amdgcn_exp2f(-g * 1.4426950408889634f); return g * u * __builtin_amdgcn_rcpf(1.0f + e); }
;     __device__ __forceinline__ void operator()(const f32x4 (&acc)[2][2][4][2], const Unit& u, int wr, int wc, int fr, int fq) const {
;         const int row0 = u.pm * BM + wr * 64 + fr; const int col0 = u.pn * HALF + wc * 32 + 8 * fq;
; #pragma unroll
;         for (int ai = 0; ai < 2; ++ai)
; #pragma unroll
;             for (int m = 0; m < 4; ++m) { const int row = row0 + ai * HALF + m * 16; bf16_t* rowp = O + (size_t)row * ldc + col0;
;                 float rs = 1.0f; if constexpr (NORM) rs = 1.0f / sqrtf(ss[row] * (1.0f / 2048.0f) + 1e-6f);
;                 const f32x4 g0 = acc[ai][0][m][0] * rs, g1 = acc[ai][0][m][1] * rs, u0 = acc[ai][1][m][0] * rs, u1 = acc[ai][1][m][1] * rs;
;                 u32x4 w; w.x = cvt_pk_bf16(act(g0[0], u0[0]), act(g0[1], u0[1])); w.y = cvt_pk_bf16(act(g0[2], u0[2]), act(g0[3], u0[3]));
;                 w.z = cvt_pk_bf16(act(g1[0], u1[0]), act(g1[1], u1[1])); w.w = cvt_pk_bf16(act(g1[2], u1[2]), act(g1[3], u1[3]));
.LBB0_1023:
	v_lshl_add_u32 v144, s0, 8, v152
	v_ashrrev_i32_e32 v145, 31, v144
	v_lshl_add_u64 v[150:151], v[144:145], 2, s[16:17]
	global_load_dword v145, v[150:151], off
	v_mov_b64_e32 v[146:147], s[14:15]
	v_lshl_or_b32 v148, s1, 7, v154
	v_mad_i64_i32 v[160:161], s[0:1], v144, s63, v[146:147]
	v_or_b32_e32 v162, 16, v144
	v_ashrrev_i32_e32 v149, 31, v148
	v_lshlrev_b64 v[148:149], 1, v[148:149]
	v_lshl_add_u64 v[160:161], v[160:161], 0, v[148:149]
	s_waitcnt vmcnt(0)
	v_fmamk_f32 v145, v145, 0x3a000000, v158
	v_rsq_f32_e32 v166, v145
	s_nop 0
	v_ashrrev_i32_e32 v163, 31, v162
	v_lshl_add_u64 v[164:165], v[162:163], 2, s[16:17]
	v_pk_mul_f32 v[126:127], v[126:127], v[166:167] op_sel_hi:[1,0]
	v_pk_mul_f32 v[124:125], v[124:125], v[166:167] op_sel_hi:[1,0]
	v_pk_mul_f32 v[122:123], v[122:123], v[166:167] op_sel_hi:[1,0]
	v_pk_mul_f32 v[120:121], v[120:121], v[166:167] op_sel_hi:[1,0]
	v_pk_mul_f32 v[118:119], v[118:119], v[166:167] op_sel_hi:[1,0]
	v_pk_mul_f32 v[116:117], v[116:117], v[166:167] op_sel_hi:[1,0]
	v_pk_mul_f32 v[114:115], v[114:115], v[166:167] op_sel_hi:[1,0]
	v_pk_mul_f32 v[112:113], v[112:113], v[166:167] op_sel_hi:[1,0]
	v_mul_f32_e32 v145, 0xbfb8aa3b, v124
	v_mul_f32_e32 v116, v124, v116
	v_mul_f32_e32 v124, 0xbfb8aa3b, v125
	v_mul_f32_e32 v117, v125, v117
	v_mul_f32_e32 v125, 0xbfb8aa3b, v126
	v_mul_f32_e32 v118, v126, v118
	v_mul_f32_e32 v126, 0xbfb8aa3b, v127
	v_mul_f32_e32 v119, v127, v119
	v_mul_f32_e32 v127, 0xbfb8aa3b, v120
	v_mul_f32_e32 v112, v120, v112
	v_mul_f32_e32 v120, 0xbfb8aa3b, v121
	v_mul_f32_e32 v113, v121, v113
	v_mul_f32_e32 v121, 0xbfb8aa3b, v122
	v_mul_f32_e32 v114, v122, v114
	v_mul_f32_e32 v122, 0xbfb8aa3b, v123
	v_exp_f32_e32 v122, v122
	v_mul_f32_e32 v115, v123, v115
	v_exp_f32_e32 v123, v145
	v_exp_f32_e32 v124, v124
	v_exp_f32_e32 v125, v125
	v_exp_f32_e32 v126, v126
	v_exp_f32_e32 v127, v127
	v_exp_f32_e32 v120, v120
	v_exp_f32_e32 v121, v121
	v_add_f32_e32 v122, 1.0, v122
	v_add_f32_e32 v123, 1.0, v123
	v_add_f32_e32 v124, 1.0, v124
	v_add_f32_e32 v125, 1.0, v125
	v_add_f32_e32 v126, 1.0, v126
	v_add_f32_e32 v127, 1.0, v127
	v_add_f32_e32 v120, 1.0, v120
	v_add_f32_e32 v121, 1.0, v121
	v_rcp_f32_e32 v122, v122
	v_rcp_f32_e32 v123, v123
	v_rcp_f32_e32 v124, v124
	v_rcp_f32_e32 v125, v125
	v_rcp_f32_e32 v126, v126
	v_rcp_f32_e32 v127, v127
	v_rcp_f32_e32 v120, v120
	v_rcp_f32_e32 v121, v121
	v_mul_f32_e32 v115, v115, v122
	v_mul_f32_e32 v116, v116, v123
	v_mul_f32_e32 v117, v117, v124
	v_mul_f32_e32 v118, v118, v125
	v_mul_f32_e32 v119, v119, v126
	v_mul_f32_e32 v123, v112, v127
	v_mul_f32_e32 v120, v113, v120
	v_mul_f32_e32 v121, v114, v121
	v_cvt_pk_bf16_f32 v112, v116, v117
	v_cvt_pk_bf16_f32 v113, v118, v119
	v_cvt_pk_bf16_f32 v114, v123, v120
	v_cvt_pk_bf16_f32 v115, v121, v115
	global_store_dwordx4 v[160:161], v[112:115], off
	global_load_dword v113, v[164:165], off
	s_nop 0
	v_or_b32_e32 v112, 32, v144
	s_waitcnt vmcnt(0)
	v_fmamk_f32 v113, v113, 0x3a000000, v158
	v_rsq_f32_e32 v118, v113
	s_nop 0
	v_mad_i64_i32 v[114:115], s[0:1], v162, s63, v[146:147]
	v_ashrrev_i32_e32 v113, 31, v112
	v_lshl_add_u64 v[114:115], v[114:115], 0, v[148:149]
	v_lshl_add_u64 v[116:117], v[112:113], 2, s[16:17]
	v_pk_mul_f32 v[110:111], v[110:111], v[118:119] op_sel_hi:[1,0]
	v_pk_mul_f32 v[108:109], v[108:109], v[118:119] op_sel_hi:[1,0]
	v_pk_mul_f32 v[106:107], v[106:107], v[118:119] op_sel_hi:[1,0]
	v_pk_mul_f32 v[104:105], v[104:105], v[118:119] op_sel_hi:[1,0]
	v_pk_mul_f32 v[102:103], v[102:103], v[118:119] op_sel_hi:[1,0]
	v_pk_mul_f32 v[100:101], v[100:101], v[118:119] op_sel_hi:[1,0]
	v_pk_mul_f32 v[98:99], v[98:99], v[118:119] op_sel_hi:[1,0]
	v_pk_mul_f32 v[96:97], v[96:97], v[118:119] op_sel_hi:[1,0]
	v_mul_f32_e32 v113, 0xbfb8aa3b, v108
	v_mul_f32_e32 v100, v108, v100
	v_mul_f32_e32 v108, 0xbfb8aa3b, v109
	v_mul_f32_e32 v101, v109, v101
	v_mul_f32_e32 v109, 0xbfb8aa3b, v110
	v_mul_f32_e32 v102, v110, v102
	v_mul_f32_e32 v110, 0xbfb8aa3b, v111
	v_mul_f32_e32 v103, v111, v103
	v_mul_f32_e32 v111, 0xbfb8aa3b, v104
	v_mul_f32_e32 v96, v104, v96
	v_mul_f32_e32 v104, 0xbfb8aa3b, v105
	v_mul_f32_e32 v97, v105, v97
	v_mul_f32_e32 v105, 0xbfb8aa3b, v106
	v_mul_f32_e32 v98, v106, v98
	v_mul_f32_e32 v106, 0xbfb8aa3b, v107
	v_exp_f32_e32 v106, v106
	v_mul_f32_e32 v99, v107, v99
	v_exp_f32_e32 v107, v113
	v_exp_f32_e32 v108, v108
	v_exp_f32_e32 v109, v109
	v_exp_f32_e32 v110, v110
	v_exp_f32_e32 v111, v111
	v_exp_f32_e32 v104, v104
	v_exp_f32_e32 v105, v105
	v_add_f32_e32 v106, 1.0, v106
	v_add_f32_e32 v107, 1.0, v107
	v_add_f32_e32 v108, 1.0, v108
	v_add_f32_e32 v109, 1.0, v109
	v_add_f32_e32 v110, 1.0, v110
	v_add_f32_e32 v111, 1.0, v111
	v_add_f32_e32 v104, 1.0, v104
	v_add_f32_e32 v105, 1.0, v105
	v_rcp_f32_e32 v106, v106
	v_rcp_f32_e32 v107, v107
	v_rcp_f32_e32 v108, v108
	v_rcp_f32_e32 v109, v109
	v_rcp_f32_e32 v110, v110
	v_rcp_f32_e32 v111, v111
	v_rcp_f32_e32 v104, v104
	v_rcp_f32_e32 v105, v105
	v_mul_f32_e32 v99, v99, v106
	v_mul_f32_e32 v100, v100, v107
	v_mul_f32_e32 v101, v101, v108
	v_mul_f32_e32 v102, v102, v109
	v_mul_f32_e32 v103, v103, v110
	v_mul_f32_e32 v107, v96, v111
	v_mul_f32_e32 v104, v97, v104
	v_mul_f32_e32 v105, v98, v105
	v_cvt_pk_bf16_f32 v96, v100, v101
	v_cvt_pk_bf16_f32 v97, v102, v103
	v_cvt_pk_bf16_f32 v98, v107, v104
	v_cvt_pk_bf16_f32 v99, v105, v99
	global_store_dwordx4 v[114:115], v[96:99], off
	global_load_dword v97, v[116:117], off
	s_nop 0
	v_or_b32_e32 v96, 48, v144
	s_waitcnt vmcnt(0)
; __device__ __forceinline__ unsigned cvt_pk_bf16(float lo, float hi) { unsigned r; asm volatile("v_cvt_pk_bf16_f32 %0, %1, %2" : "=v"(r) : "v"(lo), "v"(hi)); return r; }
;     __device__ __forceinline__ float act(float g, float u) const { const float e = __builtin_amdgcn_exp2f(-g * 1.4426950408889634f); return g * u * __builtin_amdgcn_rcpf(1.0f + e); }
;     __device__ __forceinline__ void operator()(const f32x4 (&acc)[2][2][4][2], const Unit& u, int wr, int wc, int fr, int fq) const {
;         const int row0 = u.pm * BM + wr * 64 + fr; const int col0 = u.pn * HALF + wc * 32 + 8 * fq;
; #pragma unroll
;         for (int ai = 0; ai < 2; ++ai)
; #pragma unroll
;             for (int m = 0; m < 4; ++m) { const int row = row0 + ai * HALF + m * 16; bf16_t* rowp = O + (size_t)row * ldc + col0;
;                 float rs = 1.0f; if constexpr (NORM) rs = 1.0f / sqrtf(ss[row] * (1.0f / 2048.0f) + 1e-6f);
;                 const f32x4 g0 = acc[ai][0][m][0] * rs, g1 = acc[ai][0][m][1] * rs, u0 = acc[ai][1][m][0] * rs, u1 = acc[ai][1][m][1] * rs;
;                 u32x4 w; w.x = cvt_pk_bf16(act(g0[0], u0[0]), act(g0[1], u0[1])); w.y = cvt_pk_bf16(act(g0[2], u0[2]), act(g0[3], u0[3]));
;                 w.z = cvt_pk_bf16(act(g1[0], u1[0]), act(g1[1], u1[1])); w.w = cvt_pk_bf16(act(g1[2], u1[2]), act(g1[3], u1[3]));
	v_fmamk_f32 v97, v97, 0x3a000000, v158
	v_rsq_f32_e32 v102, v97
	s_nop 0
	v_mad_i64_i32 v[98:99], s[0:1], v112, s63, v[146:147]
	v_ashrrev_i32_e32 v97, 31, v96
	v_lshl_add_u64 v[98:99], v[98:99], 0, v[148:149]
	v_lshl_add_u64 v[100:101], v[96:97], 2, s[16:17]
	v_pk_mul_f32 v[94:95], v[94:95], v[102:103] op_sel_hi:[1,0]
	v_pk_mul_f32 v[92:93], v[92:93], v[102:103] op_sel_hi:[1,0]
	v_pk_mul_f32 v[90:91], v[90:91], v[102:103] op_sel_hi:[1,0]
	v_pk_mul_f32 v[88:89], v[88:89], v[102:103] op_sel_hi:[1,0]
	v_pk_mul_f32 v[86:87], v[86:87], v[102:103] op_sel_hi:[1,0]
	v_pk_mul_f32 v[84:85], v[84:85], v[102:103] op_sel_hi:[1,0]
	v_pk_mul_f32 v[82:83], v[82:83], v[102:103] op_sel_hi:[1,0]
	v_pk_mul_f32 v[80:81], v[80:81], v[102:103] op_sel_hi:[1,0]
	v_mul_f32_e32 v97, 0xbfb8aa3b, v92
	v_mul_f32_e32 v84, v92, v84
	v_mul_f32_e32 v92, 0xbfb8aa3b, v93
	v_mul_f32_e32 v85, v93, v85
	v_mul_f32_e32 v93, 0xbfb8aa3b, v94
	v_mul_f32_e32 v86, v94, v86
	v_mul_f32_e32 v94, 0xbfb8aa3b, v95
	v_mul_f32_e32 v87, v95, v87
	v_mul_f32_e32 v95, 0xbfb8aa3b, v88
	v_mul_f32_e32 v80, v88, v80
	v_mul_f32_e32 v88, 0xbfb8aa3b, v89
	v_mul_f32_e32 v81, v89, v81
	v_mul_f32_e32 v89, 0xbfb8aa3b, v90
	v_mul_f32_e32 v82, v90, v82
	v_mul_f32_e32 v90, 0xbfb8aa3b, v91
	v_exp_f32_e32 v90, v90
	v_mul_f32_e32 v83, v91, v83
	v_exp_f32_e32 v91, v97
	v_exp_f32_e32 v92, v92
	v_exp_f32_e32 v93, v93
	v_exp_f32_e32 v94, v94
	v_exp_f32_e32 v95, v95
	v_exp_f32_e32 v88, v88
	v_exp_f32_e32 v89, v89
	v_add_f32_e32 v90, 1.0, v90
	v_add_f32_e32 v91, 1.0, v91
	v_add_f32_e32 v92, 1.0, v92
	v_add_f32_e32 v93, 1.0, v93
	v_add_f32_e32 v94, 1.0, v94
	v_add_f32_e32 v95, 1.0, v95
	v_add_f32_e32 v88, 1.0, v88
	v_add_f32_e32 v89, 1.0, v89
	v_rcp_f32_e32 v90, v90
	v_rcp_f32_e32 v91, v91
	v_rcp_f32_e32 v92, v92
	v_rcp_f32_e32 v93, v93
	v_rcp_f32_e32 v94, v94
	v_rcp_f32_e32 v95, v95
	v_rcp_f32_e32 v88, v88
	v_rcp_f32_e32 v89, v89
	v_mul_f32_e32 v83, v83, v90
	v_mul_f32_e32 v84, v84, v91
	v_mul_f32_e32 v85, v85, v92
	v_mul_f32_e32 v86, v86, v93
	v_mul_f32_e32 v87, v87, v94
	v_mul_f32_e32 v91, v80, v95
	v_mul_f32_e32 v88, v81, v88
	v_mul_f32_e32 v89, v82, v89
	v_cvt_pk_bf16_f32 v80, v84, v85
	v_cvt_pk_bf16_f32 v81, v86, v87
	v_cvt_pk_bf16_f32 v82, v91, v88
	v_cvt_pk_bf16_f32 v83, v89, v83
	global_store_dwordx4 v[98:99], v[80:83], off
	global_load_dword v80, v[100:101], off
	s_waitcnt vmcnt(0)
	v_fmamk_f32 v80, v80, 0x3a000000, v158
	v_rsq_f32_e32 v82, v80
	s_nop 0
	v_mad_i64_i32 v[80:81], s[0:1], v96, s63, v[146:147]
	v_lshl_add_u64 v[80:81], v[80:81], 0, v[148:149]
	v_pk_mul_f32 v[78:79], v[78:79], v[82:83] op_sel_hi:[1,0]
	v_pk_mul_f32 v[76:77], v[76:77], v[82:83] op_sel_hi:[1,0]
	v_pk_mul_f32 v[74:75], v[74:75], v[82:83] op_sel_hi:[1,0]
	v_pk_mul_f32 v[72:73], v[72:73], v[82:83] op_sel_hi:[1,0]
	v_pk_mul_f32 v[70:71], v[70:71], v[82:83] op_sel_hi:[1,0]
	v_pk_mul_f32 v[68:69], v[68:69], v[82:83] op_sel_hi:[1,0]
	v_pk_mul_f32 v[66:67], v[66:67], v[82:83] op_sel_hi:[1,0]
	v_pk_mul_f32 v[64:65], v[64:65], v[82:83] op_sel_hi:[1,0]
	v_mul_f32_e32 v82, 0xbfb8aa3b, v76
	v_mul_f32_e32 v68, v76, v68
	v_mul_f32_e32 v76, 0xbfb8aa3b, v77
	v_mul_f32_e32 v69, v77, v69
	v_mul_f32_e32 v77, 0xbfb8aa3b, v78
	v_mul_f32_e32 v70, v78, v70
	v_mul_f32_e32 v78, 0xbfb8aa3b, v79
	v_mul_f32_e32 v71, v79, v71
	v_mul_f32_e32 v79, 0xbfb8aa3b, v72
	v_mul_f32_e32 v64, v72, v64
	v_mul_f32_e32 v72, 0xbfb8aa3b, v73
	v_mul_f32_e32 v65, v73, v65
	v_mul_f32_e32 v73, 0xbfb8aa3b, v74
	v_mul_f32_e32 v66, v74, v66
	v_mul_f32_e32 v74, 0xbfb8aa3b, v75
	v_exp_f32_e32 v74, v74
	v_mul_f32_e32 v67, v75, v67
	v_exp_f32_e32 v75, v82
	v_exp_f32_e32 v76, v76
	v_exp_f32_e32 v77, v77
	v_exp_f32_e32 v78, v78
	v_exp_f32_e32 v79, v79
	v_exp_f32_e32 v72, v72
	v_exp_f32_e32 v73, v73
	v_add_f32_e32 v74, 1.0, v74
	v_add_f32_e32 v75, 1.0, v75
	v_add_f32_e32 v76, 1.0, v76
	v_add_f32_e32 v77, 1.0, v77
	v_add_f32_e32 v78, 1.0, v78
	v_add_f32_e32 v79, 1.0, v79
	v_add_f32_e32 v72, 1.0, v72
	v_add_f32_e32 v73, 1.0, v73
	v_rcp_f32_e32 v74, v74
	v_rcp_f32_e32 v75, v75
	v_rcp_f32_e32 v76, v76
	v_rcp_f32_e32 v77, v77
	v_rcp_f32_e32 v78, v78
	v_rcp_f32_e32 v79, v79
	v_rcp_f32_e32 v72, v72
	v_rcp_f32_e32 v73, v73
	v_mul_f32_e32 v67, v67, v74
	v_mul_f32_e32 v68, v68, v75
	v_mul_f32_e32 v69, v69, v76
	v_mul_f32_e32 v70, v70, v77
	v_mul_f32_e32 v71, v71, v78
	v_mul_f32_e32 v75, v64, v79
	v_mul_f32_e32 v72, v65, v72
	v_mul_f32_e32 v73, v66, v73
	v_cvt_pk_bf16_f32 v64, v68, v69
	v_cvt_pk_bf16_f32 v65, v70, v71
	v_cvt_pk_bf16_f32 v66, v75, v72
	v_cvt_pk_bf16_f32 v67, v73, v67
	global_store_dwordx4 v[80:81], v[64:67], off
	global_load_dword v64, v[150:151], off offset:512
	s_waitcnt vmcnt(0)
; __device__ __forceinline__ unsigned cvt_pk_bf16(float lo, float hi) { unsigned r; asm volatile("v_cvt_pk_bf16_f32 %0, %1, %2" : "=v"(r) : "v"(lo), "v"(hi)); return r; }
;     __device__ __forceinline__ float act(float g, float u) const { const float e = __builtin_amdgcn_exp2f(-g * 1.4426950408889634f); return g * u * __builtin_amdgcn_rcpf(1.0f + e); }
;     __device__ __forceinline__ void operator()(const f32x4 (&acc)[2][2][4][2], const Unit& u, int wr, int wc, int fr, int fq) const {
;         const int row0 = u.pm * BM + wr * 64 + fr; const int col0 = u.pn * HALF + wc * 32 + 8 * fq;
; #pragma unroll
;         for (int ai = 0; ai < 2; ++ai)
; #pragma unroll
;             for (int m = 0; m < 4; ++m) { const int row = row0 + ai * HALF + m * 16; bf16_t* rowp = O + (size_t)row * ldc + col0;
;                 float rs = 1.0f; if constexpr (NORM) rs = 1.0f / sqrtf(ss[row] * (1.0f / 2048.0f) + 1e-6f);
;                 const f32x4 g0 = acc[ai][0][m][0] * rs, g1 = acc[ai][0][m][1] * rs, u0 = acc[ai][1][m][0] * rs, u1 = acc[ai][1][m][1] * rs;
;                 u32x4 w; w.x = cvt_pk_bf16(act(g0[0], u0[0]), act(g0[1], u0[1])); w.y = cvt_pk_bf16(act(g0[2], u0[2]), act(g0[3], u0[3]));
;                 w.z = cvt_pk_bf16(act(g1[0], u1[0]), act(g1[1], u1[1])); w.w = cvt_pk_bf16(act(g1[2], u1[2]), act(g1[3], u1[3]));
	v_fmamk_f32 v64, v64, 0x3a000000, v158
	v_rsq_f32_e32 v66, v64
	s_nop 0
	v_add_u32_e32 v64, 0x80, v144
	v_mad_i64_i32 v[64:65], s[0:1], v64, s63, v[146:147]
	v_lshl_add_u64 v[64:65], v[64:65], 0, v[148:149]
	v_pk_mul_f32 v[62:63], v[62:63], v[66:67] op_sel_hi:[1,0]
	v_pk_mul_f32 v[60:61], v[60:61], v[66:67] op_sel_hi:[1,0]
	v_pk_mul_f32 v[58:59], v[58:59], v[66:67] op_sel_hi:[1,0]
	v_pk_mul_f32 v[56:57], v[56:57], v[66:67] op_sel_hi:[1,0]
	v_pk_mul_f32 v[54:55], v[54:55], v[66:67] op_sel_hi:[1,0]
	v_pk_mul_f32 v[52:53], v[52:53], v[66:67] op_sel_hi:[1,0]
	v_pk_mul_f32 v[50:51], v[50:51], v[66:67] op_sel_hi:[1,0]
	v_pk_mul_f32 v[48:49], v[48:49], v[66:67] op_sel_hi:[1,0]
	v_mul_f32_e32 v66, 0xbfb8aa3b, v60
	v_mul_f32_e32 v52, v60, v52
	v_mul_f32_e32 v60, 0xbfb8aa3b, v61
	v_mul_f32_e32 v53, v61, v53
	v_mul_f32_e32 v61, 0xbfb8aa3b, v62
	v_mul_f32_e32 v54, v62, v54
	v_mul_f32_e32 v62, 0xbfb8aa3b, v63
	v_mul_f32_e32 v55, v63, v55
	v_mul_f32_e32 v63, 0xbfb8aa3b, v56
	v_mul_f32_e32 v48, v56, v48
	v_mul_f32_e32 v56, 0xbfb8aa3b, v57
	v_mul_f32_e32 v49, v57, v49
	v_mul_f32_e32 v57, 0xbfb8aa3b, v58
	v_mul_f32_e32 v50, v58, v50
	v_mul_f32_e32 v58, 0xbfb8aa3b, v59
	v_exp_f32_e32 v58, v58
	v_mul_f32_e32 v51, v59, v51
	v_exp_f32_e32 v59, v66
	v_exp_f32_e32 v60, v60
	v_exp_f32_e32 v61, v61
	v_exp_f32_e32 v62, v62
	v_exp_f32_e32 v63, v63
	v_exp_f32_e32 v56, v56
	v_exp_f32_e32 v57, v57
	v_add_f32_e32 v58, 1.0, v58
	v_add_f32_e32 v59, 1.0, v59
	v_add_f32_e32 v60, 1.0, v60
	v_add_f32_e32 v61, 1.0, v61
	v_add_f32_e32 v62, 1.0, v62
	v_add_f32_e32 v63, 1.0, v63
	v_add_f32_e32 v56, 1.0, v56
	v_add_f32_e32 v57, 1.0, v57
	v_rcp_f32_e32 v58, v58
	v_rcp_f32_e32 v59, v59
	v_rcp_f32_e32 v60, v60
	v_rcp_f32_e32 v61, v61
	v_rcp_f32_e32 v62, v62
	v_rcp_f32_e32 v63, v63
	v_rcp_f32_e32 v56, v56
	v_rcp_f32_e32 v57, v57
	v_mul_f32_e32 v51, v51, v58
	v_mul_f32_e32 v52, v52, v59
	v_mul_f32_e32 v53, v53, v60
	v_mul_f32_e32 v54, v54, v61
	v_mul_f32_e32 v55, v55, v62
	v_mul_f32_e32 v59, v48, v63
	v_mul_f32_e32 v56, v49, v56
	v_mul_f32_e32 v57, v50, v57
	v_cvt_pk_bf16_f32 v48, v52, v53
	v_cvt_pk_bf16_f32 v49, v54, v55
	v_cvt_pk_bf16_f32 v50, v59, v56
	v_cvt_pk_bf16_f32 v51, v57, v51
	global_store_dwordx4 v[64:65], v[48:51], off
	global_load_dword v48, v[150:151], off offset:576
	s_waitcnt vmcnt(0)
	v_fmamk_f32 v48, v48, 0x3a000000, v158
	v_rsq_f32_e32 v50, v48
	s_nop 0
	v_add_u32_e32 v48, 0x90, v144
	v_mad_i64_i32 v[48:49], s[0:1], v48, s63, v[146:147]
	v_lshl_add_u64 v[48:49], v[48:49], 0, v[148:149]
	v_pk_mul_f32 v[46:47], v[46:47], v[50:51] op_sel_hi:[1,0]
	v_pk_mul_f32 v[44:45], v[44:45], v[50:51] op_sel_hi:[1,0]
	v_pk_mul_f32 v[42:43], v[42:43], v[50:51] op_sel_hi:[1,0]
	v_pk_mul_f32 v[40:41], v[40:41], v[50:51] op_sel_hi:[1,0]
	v_pk_mul_f32 v[38:39], v[38:39], v[50:51] op_sel_hi:[1,0]
	v_pk_mul_f32 v[36:37], v[36:37], v[50:51] op_sel_hi:[1,0]
	v_pk_mul_f32 v[34:35], v[34:35], v[50:51] op_sel_hi:[1,0]
	v_pk_mul_f32 v[32:33], v[32:33], v[50:51] op_sel_hi:[1,0]
	v_mul_f32_e32 v50, 0xbfb8aa3b, v44
	v_mul_f32_e32 v36, v44, v36
	v_mul_f32_e32 v44, 0xbfb8aa3b, v45
	v_mul_f32_e32 v37, v45, v37
	v_mul_f32_e32 v45, 0xbfb8aa3b, v46
	v_mul_f32_e32 v38, v46, v38
	v_mul_f32_e32 v46, 0xbfb8aa3b, v47
	v_mul_f32_e32 v39, v47, v39
	v_mul_f32_e32 v47, 0xbfb8aa3b, v40
	v_mul_f32_e32 v32, v40, v32
	v_mul_f32_e32 v40, 0xbfb8aa3b, v41
	v_mul_f32_e32 v33, v41, v33
	v_mul_f32_e32 v41, 0xbfb8aa3b, v42
	v_mul_f32_e32 v34, v42, v34
	v_mul_f32_e32 v42, 0xbfb8aa3b, v43
	v_exp_f32_e32 v42, v42
	v_mul_f32_e32 v35, v43, v35
	v_exp_f32_e32 v43, v50
	v_exp_f32_e32 v44, v44
	v_exp_f32_e32 v45, v45
	v_exp_f32_e32 v46, v46
	v_exp_f32_e32 v47, v47
	v_exp_f32_e32 v40, v40
	v_exp_f32_e32 v41, v41
	v_add_f32_e32 v42, 1.0, v42
	v_add_f32_e32 v43, 1.0, v43
	v_add_f32_e32 v44, 1.0, v44
	v_add_f32_e32 v45, 1.0, v45
	v_add_f32_e32 v46, 1.0, v46
	v_add_f32_e32 v47, 1.0, v47
	v_add_f32_e32 v40, 1.0, v40
	v_add_f32_e32 v41, 1.0, v41
	v_rcp_f32_e32 v42, v42
	v_rcp_f32_e32 v43, v43
	v_rcp_f32_e32 v44, v44
	v_rcp_f32_e32 v45, v45
	v_rcp_f32_e32 v46, v46
	v_rcp_f32_e32 v47, v47
	v_rcp_f32_e32 v40, v40
	v_rcp_f32_e32 v41, v41
	v_mul_f32_e32 v35, v35, v42
	v_mul_f32_e32 v36, v36, v43
	v_mul_f32_e32 v37, v37, v44
	v_mul_f32_e32 v38, v38, v45
	v_mul_f32_e32 v39, v39, v46
	v_mul_f32_e32 v43, v32, v47
	v_mul_f32_e32 v40, v33, v40
	v_mul_f32_e32 v41, v34, v41
	v_cvt_pk_bf16_f32 v32, v36, v37
	v_cvt_pk_bf16_f32 v33, v38, v39
	v_cvt_pk_bf16_f32 v34, v43, v40
	v_cvt_pk_bf16_f32 v35, v41, v35
	global_store_dwordx4 v[48:49], v[32:35], off
	global_load_dword v32, v[150:151], off offset:640
	s_waitcnt vmcnt(0)
; __device__ __forceinline__ unsigned cvt_pk_bf16(float lo, float hi) { unsigned r; asm volatile("v_cvt_pk_bf16_f32 %0, %1, %2" : "=v"(r) : "v"(lo), "v"(hi)); return r; }
;     __device__ __forceinline__ float act(float g, float u) const { const float e = __builtin_amdgcn_exp2f(-g * 1.4426950408889634f); return g * u * __builtin_amdgcn_rcpf(1.0f + e); }
; #define PG8_BAR __builtin_amdgcn_s_barrier()
;     __device__ __forceinline__ void operator()(const f32x4 (&acc)[2][2][4][2], const Unit& u, int wr, int wc, int fr, int fq) const {
;         const int row0 = u.pm * BM + wr * 64 + fr; const int col0 = u.pn * HALF + wc * 32 + 8 * fq;
; #pragma unroll
;         for (int ai = 0; ai < 2; ++ai)
; #pragma unroll
;             for (int m = 0; m < 4; ++m) { const int row = row0 + ai * HALF + m * 16; bf16_t* rowp = O + (size_t)row * ldc + col0;
;                 float rs = 1.0f; if constexpr (NORM) rs = 1.0f / sqrtf(ss[row] * (1.0f / 2048.0f) + 1e-6f);
;                 const f32x4 g0 = acc[ai][0][m][0] * rs, g1 = acc[ai][0][m][1] * rs, u0 = acc[ai][1][m][0] * rs, u1 = acc[ai][1][m][1] * rs;
;                 u32x4 w; w.x = cvt_pk_bf16(act(g0[0], u0[0]), act(g0[1], u0[1])); w.y = cvt_pk_bf16(act(g0[2], u0[2]), act(g0[3], u0[3]));
;                 w.z = cvt_pk_bf16(act(g1[0], u1[0]), act(g1[1], u1[1])); w.w = cvt_pk_bf16(act(g1[2], u1[2]), act(g1[3], u1[3]));
;                 *(u32x4*)rowp = w; }
; template <class Epi, class Sched, bool ALIGN_EPI = false, bool SP2 = false>
; __device__ __forceinline__ void gemm_phase(PG8_LAS unsigned char* lds, const Gemm g, const Sched& S, const Epi& E) {
;     ...
;         if (!has_next) break;
; #pragma unroll
;         for (int a = 0; a < 2; ++a)
; #pragma unroll
;             for (int b = 0; b < 2; ++b)
; #pragma unroll
;                 for (int m = 0; m < 4; ++m)
; #pragma unroll
;                     for (int n = 0; n < 2; ++n) acc[a][b][m][n] = (f32x4){0.f, 0.f, 0.f, 0.f};
;         cur = nxt; cA = nA; cB = nB; ++ui;
;         if constexpr (ALIGN_EPI) { if (wr == 1) PG8_BAR; }
	v_fmamk_f32 v32, v32, 0x3a000000, v158
	v_rsq_f32_e32 v34, v32
	s_nop 0
	v_add_u32_e32 v32, 0xa0, v144
	v_mad_i64_i32 v[32:33], s[0:1], v32, s63, v[146:147]
	v_lshl_add_u64 v[32:33], v[32:33], 0, v[148:149]
	v_pk_mul_f32 v[30:31], v[30:31], v[34:35] op_sel_hi:[1,0]
	v_pk_mul_f32 v[28:29], v[28:29], v[34:35] op_sel_hi:[1,0]
	v_pk_mul_f32 v[26:27], v[26:27], v[34:35] op_sel_hi:[1,0]
	v_pk_mul_f32 v[24:25], v[24:25], v[34:35] op_sel_hi:[1,0]
	v_pk_mul_f32 v[22:23], v[22:23], v[34:35] op_sel_hi:[1,0]
	v_pk_mul_f32 v[20:21], v[20:21], v[34:35] op_sel_hi:[1,0]
	v_pk_mul_f32 v[18:19], v[18:19], v[34:35] op_sel_hi:[1,0]
	v_pk_mul_f32 v[16:17], v[16:17], v[34:35] op_sel_hi:[1,0]
	v_mul_f32_e32 v34, 0xbfb8aa3b, v28
	v_mul_f32_e32 v20, v28, v20
	v_mul_f32_e32 v28, 0xbfb8aa3b, v29
	v_mul_f32_e32 v21, v29, v21
	v_mul_f32_e32 v29, 0xbfb8aa3b, v30
	v_mul_f32_e32 v22, v30, v22
	v_mul_f32_e32 v30, 0xbfb8aa3b, v31
	v_mul_f32_e32 v23, v31, v23
	v_mul_f32_e32 v31, 0xbfb8aa3b, v24
	v_mul_f32_e32 v16, v24, v16
	v_mul_f32_e32 v24, 0xbfb8aa3b, v25
	v_mul_f32_e32 v17, v25, v17
	v_mul_f32_e32 v25, 0xbfb8aa3b, v26
	v_mul_f32_e32 v18, v26, v18
	v_mul_f32_e32 v26, 0xbfb8aa3b, v27
	v_exp_f32_e32 v26, v26
	v_mul_f32_e32 v19, v27, v19
	v_exp_f32_e32 v27, v34
	v_exp_f32_e32 v28, v28
	v_exp_f32_e32 v29, v29
	v_exp_f32_e32 v30, v30
	v_exp_f32_e32 v31, v31
	v_exp_f32_e32 v24, v24
	v_exp_f32_e32 v25, v25
	v_add_f32_e32 v26, 1.0, v26
	v_add_f32_e32 v27, 1.0, v27
	v_add_f32_e32 v28, 1.0, v28
	v_add_f32_e32 v29, 1.0, v29
	v_add_f32_e32 v30, 1.0, v30
	v_add_f32_e32 v31, 1.0, v31
	v_add_f32_e32 v24, 1.0, v24
	v_add_f32_e32 v25, 1.0, v25
	v_rcp_f32_e32 v26, v26
	v_rcp_f32_e32 v27, v27
	v_rcp_f32_e32 v28, v28
	v_rcp_f32_e32 v29, v29
	v_rcp_f32_e32 v30, v30
	v_rcp_f32_e32 v31, v31
	v_rcp_f32_e32 v24, v24
	v_rcp_f32_e32 v25, v25
	v_mul_f32_e32 v19, v19, v26
	v_mul_f32_e32 v20, v20, v27
	v_mul_f32_e32 v21, v21, v28
	v_mul_f32_e32 v22, v22, v29
	v_mul_f32_e32 v23, v23, v30
	v_mul_f32_e32 v27, v16, v31
	v_mul_f32_e32 v24, v17, v24
	v_mul_f32_e32 v25, v18, v25
	v_cvt_pk_bf16_f32 v16, v20, v21
	v_cvt_pk_bf16_f32 v17, v22, v23
	v_cvt_pk_bf16_f32 v18, v27, v24
	v_cvt_pk_bf16_f32 v19, v25, v19
	global_store_dwordx4 v[32:33], v[16:19], off
	global_load_dword v16, v[150:151], off offset:704
	s_nop 0
	v_add_u32_e32 v17, 0xb0, v144
	s_waitcnt vmcnt(0)
	v_fmamk_f32 v16, v16, 0x3a000000, v158
	v_rsq_f32_e32 v18, v16
	s_nop 0
	v_mad_i64_i32 v[16:17], s[0:1], v17, s63, v[146:147]
	v_lshl_add_u64 v[16:17], v[16:17], 0, v[148:149]
	s_mov_b64 s[0:1], -1
	v_pk_mul_f32 v[14:15], v[14:15], v[18:19] op_sel_hi:[1,0]
	v_pk_mul_f32 v[12:13], v[12:13], v[18:19] op_sel_hi:[1,0]
	v_pk_mul_f32 v[10:11], v[10:11], v[18:19] op_sel_hi:[1,0]
	v_pk_mul_f32 v[8:9], v[8:9], v[18:19] op_sel_hi:[1,0]
	v_pk_mul_f32 v[6:7], v[6:7], v[18:19] op_sel_hi:[1,0]
	v_pk_mul_f32 v[4:5], v[4:5], v[18:19] op_sel_hi:[1,0]
	v_pk_mul_f32 v[2:3], v[2:3], v[18:19] op_sel_hi:[1,0]
	v_pk_mul_f32 v[0:1], v[0:1], v[18:19] op_sel_hi:[1,0]
	v_mul_f32_e32 v18, 0xbfb8aa3b, v12
	v_mul_f32_e32 v4, v12, v4
	v_mul_f32_e32 v12, 0xbfb8aa3b, v13
	v_mul_f32_e32 v5, v13, v5
	v_mul_f32_e32 v13, 0xbfb8aa3b, v14
	v_mul_f32_e32 v6, v14, v6
	v_mul_f32_e32 v14, 0xbfb8aa3b, v15
	v_mul_f32_e32 v7, v15, v7
	v_mul_f32_e32 v15, 0xbfb8aa3b, v8
	v_mul_f32_e32 v0, v8, v0
	v_mul_f32_e32 v8, 0xbfb8aa3b, v9
	v_mul_f32_e32 v1, v9, v1
	v_mul_f32_e32 v9, 0xbfb8aa3b, v10
	v_mul_f32_e32 v2, v10, v2
	v_mul_f32_e32 v10, 0xbfb8aa3b, v11
	v_exp_f32_e32 v10, v10
	v_mul_f32_e32 v3, v11, v3
	v_exp_f32_e32 v11, v18
	v_exp_f32_e32 v12, v12
	v_exp_f32_e32 v13, v13
	v_exp_f32_e32 v14, v14
	v_exp_f32_e32 v15, v15
	v_exp_f32_e32 v8, v8
	v_exp_f32_e32 v9, v9
	v_add_f32_e32 v10, 1.0, v10
	v_add_f32_e32 v11, 1.0, v11
	v_add_f32_e32 v12, 1.0, v12
	v_add_f32_e32 v13, 1.0, v13
	v_add_f32_e32 v14, 1.0, v14
	v_add_f32_e32 v15, 1.0, v15
	v_add_f32_e32 v8, 1.0, v8
	v_add_f32_e32 v9, 1.0, v9
	v_rcp_f32_e32 v10, v10
	v_rcp_f32_e32 v11, v11
	v_rcp_f32_e32 v12, v12
	v_rcp_f32_e32 v13, v13
	v_rcp_f32_e32 v14, v14
	v_rcp_f32_e32 v15, v15
	v_rcp_f32_e32 v8, v8
	v_rcp_f32_e32 v9, v9
	s_andn2_b64 vcc, exec, s[2:3]
	v_mul_f32_e32 v3, v3, v10
	v_mul_f32_e32 v4, v4, v11
	v_mul_f32_e32 v5, v5, v12
	v_mul_f32_e32 v6, v6, v13
	v_mul_f32_e32 v7, v7, v14
	v_mul_f32_e32 v11, v0, v15
	v_mul_f32_e32 v8, v1, v8
	v_mul_f32_e32 v9, v2, v9
	v_cvt_pk_bf16_f32 v0, v4, v5
	v_cvt_pk_bf16_f32 v1, v6, v7
	v_cvt_pk_bf16_f32 v2, v11, v8
	v_cvt_pk_bf16_f32 v3, v9, v3
	global_store_dwordx4 v[16:17], v[0:3], off
	s_cbranch_vccnz .LBB0_1016
	s_andn2_b64 vcc, exec, s[12:13]
	s_cbranch_vccnz .LBB0_1015
	s_barrier
	s_branch .LBB0_1015
